# hg_b phase B rewritten by hand: q_dec tiles via coalesced LDS DMA into a swizzled per-wave two-slot ring, tiles prefetched two ahead
# speedup vs baseline: 1.0078x; 1.0078x over previous
; #define LAS __attribute__((address_space(3)))
; __device__ __forceinline__ void hg_b_item(const Params& p, LAS unsigned char* lds, int item, bool dry = false) {
;     ...
;     LAS bf16_t* SB = (LAS bf16_t*)lds;
;     const int b = item >> 6, h = (item >> 3) & 7, es = item & 7;
;     const int fr = lane & 15, fq = lane >> 4;
;     const bf16_t* Z = (const bf16_t*)(WSP + WS_Z); bf16_t* OI = (bf16_t*)(WSP + WS_OI); const float* DEC = (const float*)(WSP + WS_DEC);
;     f32x4 S = (f32x4){0.f, 0.f, 0.f, 0.f};
;     const int eg = 16 * es + fr, dg = 16 * wave + fr;
;     const bf16_t* pV = Z + (size_t)(b * SEQ + (eg >> 1)) * ZW + 4096 + h * 128 + (eg & 1) * 64 + 8 * fq;
;     const bf16_t* pK = Z + (size_t)(b * SEQ + (dg >> 1)) * ZW + 3072 + h * 128 + (dg & 1) * 64 + 8 * fq;
;     const bf16_t* pQ = Z + (size_t)(b * SEQ + fr) * ZW + 2048 + h * 128 + 8 * fq;
;     bf16_t* pO = OI + (size_t)(b * SEQ + 4 * fq) * D + h * 128 + 16 * es + fr;
;     const float* pD = DEC + (size_t)((b * 8 + h) * 64) * 128 + dg;
;     __syncthreads();
.LBB0_202:
	s_lshl_b32 s4, s50, 3
	s_and_b32 s4, s4, 56
	s_and_b32 s5, s50, 0xffffffc0
	s_or_b32 s4, s4, s5
	s_bfe_u32 s5, s50, 0x30003
	s_or_b32 s8, s4, s5
	s_and_b64 s[4:5], s[6:7], exec
	v_readfirstlane_b32 s24, v34
	v_readfirstlane_b32 s25, v35
	v_mov_b32_e32 v3, v162
	s_cselect_b32 s4, s8, s50
	v_readfirstlane_b32 s5, v3
	s_ashr_i32 s51, s5, 6
	v_and_b32_e32 v8, 15, v3
	s_ashr_i32 s16, s4, 6
	v_lshl_or_b32 v2, s51, 4, v8
	s_lshl_b32 s55, s16, 12
	v_ashrrev_i32_e32 v0, 1, v2
	s_bfe_u32 s17, s4, 0x30003
	s_lshl_b32 s4, s4, 4
	v_add_u32_e32 v0, s55, v0
	s_and_b32 s54, s4, 0x70
	v_mad_i64_i32 v[22:23], s[4:5], v0, s3, 0
	v_or_b32_e32 v0, s55, v8
	v_mov_b64_e32 v[4:5], s[24:25]
	v_bfe_u32 v9, v3, 4, 2
	v_mad_i64_i32 v[4:5], s[4:5], v0, s3, v[4:5]
	s_lshl_b32 s8, s17, 8
	v_lshl_add_u64 v[4:5], v[4:5], 0, s[8:9]
	v_lshlrev_b32_e32 v0, 4, v9
	v_lshl_add_u64 v[4:5], v[4:5], 0, v[0:1]
	v_lshl_add_u64 v[24:25], v[4:5], 0, s[10:11]
	v_lshl_or_b32 v4, v9, 2, s55
	v_ashrrev_i32_e32 v5, 31, v4
	v_lshlrev_b64 v[4:5], 11, v[4:5]
	v_lshl_add_u64 v[4:5], s[24:25], 0, v[4:5]
	v_lshl_add_u64 v[4:5], v[4:5], 0, s[8:9]
	s_lshl_b32 s4, s54, 1
	s_mov_b32 s5, s9
	v_lshl_add_u64 v[4:5], v[4:5], 0, s[4:5]
	v_lshlrev_b32_e32 v6, 1, v8
	v_mov_b32_e32 v7, v1
	v_lshl_add_u64 v[4:5], v[4:5], 0, v[6:7]
	v_lshl_add_u64 v[26:27], v[4:5], 0, s[12:13]
	v_or_b32_e32 v5, s54, v8
	v_lshrrev_b16_e32 v5, 1, v5
	v_or_b32_e32 v5, s55, v5
	v_mad_i64_i32 v[28:29], s[4:5], v5, s3, 0
	v_lshlrev_b32_e32 v3, 7, v3
	v_or_b32_e32 v5, s8, v28
	v_and_b32_e32 v3, 0x80, v3
	s_lshl_b32 s16, s16, 9
	s_lshl_b32 s17, s17, 6
	v_mul_u32_u24_e32 v4, 0x110, v8
	v_or3_b32 v28, v5, v3, v0
	v_or_b32_e32 v5, s8, v22
	s_lshl_b32 s4, s51, 5
	v_add3_u32 v4, 0, v0, v4
	v_or3_b32 v22, v5, v3, v0
	v_mov_b32_e32 v0, s4
	s_or_b32 s4, s16, s17
	s_ashr_i32 s5, s4, 31
	v_mad_u32_u24 v0, v9, s26, v0
	s_lshl_b64 s[4:5], s[4:5], 9
	v_ashrrev_i32_e32 v3, 31, v2
	s_mul_i32 s56, s51, 0x1100
	v_or_b32_e32 v0, v0, v6
	v_lshl_add_u64 v[30:31], v[2:3], 2, s[4:5]
	v_mov_b32_e32 v2, v1
	v_mov_b32_e32 v3, v1
	v_add_u32_e32 v37, 0, v0
	v_mov_b32_e32 v0, v1
	v_add_u32_e32 v38, s56, v4
	v_mov_b64_e32 v[4:5], v[2:3]
	v_mov_b64_e32 v[2:3], v[0:1]
	v_lshrrev_b32_e32 v174, 4, v162
	v_and_b32_e32 v174, 7, v174
	v_and_b32_e32 v175, 15, v162
	s_lshr_b32 s98, s54, 1
	s_add_i32 s98, s98, s55
	v_add_u32_e32 v176, s98, v174
	v_mul_u32_u24_e32 v176, 0x3000, v176
	v_lshl_add_u32 v176, v175, 4, v176
	v_add_u32_e32 v176, s8, v176
	v_lshrrev_b32_e32 v177, 7, v162
	v_mul_u32_u24_e32 v170, 0xc0000, v177
	v_add_u32_e32 v170, v170, v176
	v_add_u32_e32 v170, 0x402000, v170
	global_load_dwordx4 v[80:83], v170, s[24:25]
	v_add_u32_e32 v96, 0x300000, v170
	global_load_dwordx4 v[84:87], v96, s[24:25]
	v_add_u32_e32 v97, 0x600000, v170
	global_load_dwordx4 v[88:91], v97, s[24:25]
	v_add_u32_e32 v98, 0x900000, v170
	global_load_dwordx4 v[92:95], v98, s[24:25]
	v_add_u32_e32 v170, 0xc00000, v170
	v_mul_u32_u24_e32 v171, 0x1100, v177
	v_lshrrev_b32_e32 v177, 3, v175
	v_lshl_add_u32 v177, v174, 1, v177
	v_mul_u32_u24_e32 v177, 0x90, v177
	v_and_b32_e32 v174, 7, v175
	v_lshl_add_u32 v177, v174, 4, v177
	v_add_u32_e32 v171, v171, v177
	v_add_u32_e32 v171, 0x12000, v171
	v_and_b32_e32 v174, 15, v162
	v_bfe_u32 v175, v162, 4, 2
	v_mul_u32_u24_e32 v172, 0x90, v174
	v_lshl_add_u32 v172, v175, 4, v172
	v_add_u32_e32 v172, 0x12000, v172
	s_waitcnt vmcnt(0)
	ds_write_b128 v171, v[80:83]
	ds_write_b128 v171, v[84:87] offset:17408
	ds_write_b128 v171, v[88:91] offset:34816
	ds_write_b128 v171, v[92:95] offset:52224
	s_waitcnt lgkmcnt(0)
	s_mul_i32 s99, s55, 0x3000
	s_add_i32 s99, s99, s8
	s_add_i32 s99, s99, 0x401000
	v_and_b32_e32 v174, 15, v162
	v_bfe_u32 v175, v162, 4, 2
	v_xor_b32_e32 v176, v174, v175
	v_lshlrev_b32_e32 v176, 4, v176
	v_mul_u32_u24_e32 v177, 0x3000, v175
	v_add_u32_e32 v178, v177, v176
	v_xor_b32_e32 v179, 64, v176
	v_add_u32_e32 v179, v179, v177
	v_add_u32_e32 v179, 0xc000, v179
	v_xor_b32_e32 v180, 128, v176
	v_add_u32_e32 v180, v180, v177
	v_add_u32_e32 v180, 0x18000, v180
	v_xor_b32_e32 v181, 192, v176
	v_add_u32_e32 v181, v181, v177
	v_add_u32_e32 v181, 0x24000, v181
	s_lshl_b32 s98, s51, 13
	s_add_i32 s98, s98, 0x12000
	v_lshlrev_b32_e32 v177, 8, v174
	v_add_u32_e32 v177, s98, v177
	v_add_u32_e32 v182, v177, v176
	v_xor_b32_e32 v183, 64, v176
	v_add_u32_e32 v183, v183, v177
	v_xor_b32_e32 v184, 128, v176
	v_add_u32_e32 v184, v184, v177
	v_xor_b32_e32 v185, 192, v176
	v_add_u32_e32 v185, v185, v177
	s_mov_b32 s8, 0
	s_barrier

; #define LAS __attribute__((address_space(3)))
; __device__ __forceinline__ unsigned f2bf(float f) { unsigned u = __float_as_uint(f); return (u + 0x7fffu + ((u >> 16) & 1u)) >> 16; }
; __device__ __forceinline__ float bf2f(unsigned h) { return __uint_as_float(h << 16); }
; #define MFMA16(a, b, c) __builtin_amdgcn_mfma_f32_16x16x32_bf16((a), (b), (c), 0, 0, 0)
; __device__ __forceinline__ void hg_b_item(const Params& p, LAS unsigned char* lds, int item, bool dry = false) {
;     ...
;         for (int c2 = 0; c2 < 2; ++c2) { const int g = wave + 8 * c2, nB = 16 * G16 + g; const size_t roB = (size_t)nB * 64 * ZW;
;             bf16x8 bS[4];
; #pragma unroll
;             for (int k = 0; k < 4; ++k) bS[k] = *(const LAS bf16x8*)(SB + g * 2176 + fr * 136 + 32 * k + 8 * fq);
; #pragma unroll
;             for (int lt = 0; lt < 4; ++lt) { f32x4 acc = (f32x4){0.f, 0.f, 0.f, 0.f}; unsigned short oO[4];
; #pragma unroll
;                 for (int r = 0; r < 4; ++r) oO[r] = pO[(size_t)(nB * 64 + 16 * lt + r) * D];
; #pragma unroll
;                 for (int k = 0; k < 4; ++k) { const bf16x8 a = *(const bf16x8*)(pQ + roB + (size_t)(16 * lt) * ZW + 32 * k); acc = MFMA16(a, bS[k], acc); }
; #pragma unroll
;                 for (int r = 0; r < 4; ++r) { const float nv = bf2f(oO[r]) + acc[r]; if (!dry) pO[(size_t)(nB * 64 + 16 * lt + r) * D] = (bf16_t)f2bf(nv); else if (nv == 123456.0f) pO[0] = 0; } } }
.Lhgb_nostage:
	s_lshl_b32 s4, s8, 4
	s_add_i32 s4, s4, s51
	s_mul_i32 s5, s4, 0xc0000
	s_add_i32 s5, s5, s99
	s_add_u32 s54, s24, s5
	s_addc_u32 s55, s25, 0
	s_lshl_b32 s56, s4, 17
	s_add_i32 s56, s56, 0x1000
	s_mov_b32 s57, 0
	s_add_i32 s8, s8, 1
	v_lshl_add_u64 v[28:29], v[28:29], 0, s[20:21]
	v_lshl_add_u64 v[22:23], v[22:23], 0, s[20:21]
	v_lshl_add_u64 v[30:31], v[30:31], 0, s[22:23]
	s_lshl_b32 s58, s51, 13
	s_add_i32 s58, s58, 0x12000
	s_mov_b32 s60, s54
	s_mov_b32 s61, s55
	s_add_i32 m0, s58, 0x0
	s_nop 0
	global_load_lds_dwordx4 v178, s[60:61]
	s_add_i32 m0, s58, 0x400
	s_nop 0
	global_load_lds_dwordx4 v179, s[60:61]
	s_add_i32 m0, s58, 0x800
	s_nop 0
	global_load_lds_dwordx4 v180, s[60:61]
	s_add_i32 m0, s58, 0xc00
	s_nop 0
	global_load_lds_dwordx4 v181, s[60:61]
	s_mov_b32 s16, s56
	s_mov_b32 s17, s57
	v_lshl_add_u64 v[108:109], v[26:27], 0, s[16:17]
	global_load_ushort v100, v[108:109], off offset:-4096
	global_load_ushort v101, v[108:109], off offset:-2048
	global_load_ushort v102, v[108:109], off
	global_load_ushort v103, v[108:109], off offset:2048
	s_add_u32 s60, s54, 0x30000
	s_addc_u32 s61, s55, 0
	s_add_i32 m0, s58, 0x1000
	s_nop 0
	global_load_lds_dwordx4 v178, s[60:61]
	s_add_i32 m0, s58, 0x1400
	s_nop 0
	global_load_lds_dwordx4 v179, s[60:61]
	s_add_i32 m0, s58, 0x1800
	s_nop 0
	global_load_lds_dwordx4 v180, s[60:61]
	s_add_i32 m0, s58, 0x1c00
	s_nop 0
	global_load_lds_dwordx4 v181, s[60:61]
	s_add_u32 s16, s56, 0x8000
	s_addc_u32 s17, s57, 0
	v_lshl_add_u64 v[110:111], v[26:27], 0, s[16:17]
	global_load_ushort v104, v[110:111], off offset:-4096
	global_load_ushort v105, v[110:111], off offset:-2048
	global_load_ushort v106, v[110:111], off
	global_load_ushort v107, v[110:111], off offset:2048
	ds_read_b128 v[40:43], v38
	ds_read_b128 v[44:47], v38 offset:64
	ds_read_b128 v[48:51], v38 offset:128
	ds_read_b128 v[52:55], v38 offset:192
	s_waitcnt vmcnt(8)
	ds_read_b128 v[56:59], v182
	ds_read_b128 v[60:63], v183
	ds_read_b128 v[64:67], v184
	ds_read_b128 v[68:71], v185
	s_waitcnt lgkmcnt(0)
	v_mfma_f32_16x16x32_bf16 v[72:75], v[56:59], v[40:43], 0
	v_mfma_f32_16x16x32_bf16 v[72:75], v[60:63], v[44:47], v[72:75]
	v_mfma_f32_16x16x32_bf16 v[72:75], v[64:67], v[48:51], v[72:75]
	v_mfma_f32_16x16x32_bf16 v[72:75], v[68:71], v[52:55], v[72:75]
	v_lshlrev_b32_e32 v100, 16, v100
	v_lshlrev_b32_e32 v101, 16, v101
	v_lshlrev_b32_e32 v102, 16, v102
	v_lshlrev_b32_e32 v103, 16, v103
	s_nop 7
	v_add_f32_e32 v112, v72, v100
	v_add_f32_e32 v113, v73, v101
	v_add_f32_e32 v114, v74, v102
	v_add_f32_e32 v115, v75, v103
	v_bfe_u32 v116, v112, 16, 1
	v_bfe_u32 v117, v113, 16, 1
	v_bfe_u32 v118, v114, 16, 1
	v_bfe_u32 v119, v115, 16, 1
	v_add3_u32 v112, v112, v116, s27
	v_add3_u32 v113, v113, v117, s27
	v_add3_u32 v114, v114, v118, s27
	v_add3_u32 v115, v115, v119, s27
	global_store_short_d16_hi v[108:109], v112, off offset:-4096
	global_store_short_d16_hi v[108:109], v113, off offset:-2048
	global_store_short_d16_hi v[108:109], v114, off
	global_store_short_d16_hi v[108:109], v115, off offset:2048
	s_add_u32 s60, s54, 0x60000
	s_addc_u32 s61, s55, 0
	s_add_i32 m0, s58, 0x0
	s_nop 0
	global_load_lds_dwordx4 v178, s[60:61]
	s_add_i32 m0, s58, 0x400
	s_nop 0
	global_load_lds_dwordx4 v179, s[60:61]
	s_add_i32 m0, s58, 0x800
	s_nop 0
	global_load_lds_dwordx4 v180, s[60:61]
	s_add_i32 m0, s58, 0xc00
	s_nop 0
	global_load_lds_dwordx4 v181, s[60:61]
	s_add_u32 s16, s56, 0x10000
	s_addc_u32 s17, s57, 0
	v_lshl_add_u64 v[108:109], v[26:27], 0, s[16:17]
	global_load_ushort v100, v[108:109], off offset:-4096
	global_load_ushort v101, v[108:109], off offset:-2048
	global_load_ushort v102, v[108:109], off
	global_load_ushort v103, v[108:109], off offset:2048
	s_waitcnt vmcnt(12)
	ds_read_b128 v[56:59], v182 offset:4096
	ds_read_b128 v[60:63], v183 offset:4096
	ds_read_b128 v[64:67], v184 offset:4096
	ds_read_b128 v[68:71], v185 offset:4096
	s_waitcnt lgkmcnt(0)
	v_mfma_f32_16x16x32_bf16 v[72:75], v[56:59], v[40:43], 0
	v_mfma_f32_16x16x32_bf16 v[72:75], v[60:63], v[44:47], v[72:75]
	v_mfma_f32_16x16x32_bf16 v[72:75], v[64:67], v[48:51], v[72:75]
	v_mfma_f32_16x16x32_bf16 v[72:75], v[68:71], v[52:55], v[72:75]
	v_lshlrev_b32_e32 v104, 16, v104
	v_lshlrev_b32_e32 v105, 16, v105
	v_lshlrev_b32_e32 v106, 16, v106
	v_lshlrev_b32_e32 v107, 16, v107
	s_nop 7
	v_add_f32_e32 v112, v72, v104
	v_add_f32_e32 v113, v73, v105
	v_add_f32_e32 v114, v74, v106
	v_add_f32_e32 v115, v75, v107
	v_bfe_u32 v116, v112, 16, 1
	v_bfe_u32 v117, v113, 16, 1
	v_bfe_u32 v118, v114, 16, 1
	v_bfe_u32 v119, v115, 16, 1
	v_add3_u32 v112, v112, v116, s27
	v_add3_u32 v113, v113, v117, s27
	v_add3_u32 v114, v114, v118, s27
	v_add3_u32 v115, v115, v119, s27
	global_store_short_d16_hi v[110:111], v112, off offset:-4096
	global_store_short_d16_hi v[110:111], v113, off offset:-2048
	global_store_short_d16_hi v[110:111], v114, off
	global_store_short_d16_hi v[110:111], v115, off offset:2048
	s_add_u32 s60, s54, 0x90000
	s_addc_u32 s61, s55, 0
	s_add_i32 m0, s58, 0x1000
	s_nop 0
	global_load_lds_dwordx4 v178, s[60:61]
	s_add_i32 m0, s58, 0x1400
	s_nop 0
	global_load_lds_dwordx4 v179, s[60:61]
	s_add_i32 m0, s58, 0x1800
	s_nop 0
	global_load_lds_dwordx4 v180, s[60:61]
	s_add_i32 m0, s58, 0x1c00
	s_nop 0
	global_load_lds_dwordx4 v181, s[60:61]
	s_add_u32 s16, s56, 0x18000
	s_addc_u32 s17, s57, 0
	v_lshl_add_u64 v[110:111], v[26:27], 0, s[16:17]
	global_load_ushort v104, v[110:111], off offset:-4096
	global_load_ushort v105, v[110:111], off offset:-2048
	global_load_ushort v106, v[110:111], off
	global_load_ushort v107, v[110:111], off offset:2048
	s_waitcnt vmcnt(12)
; #define LAS __attribute__((address_space(3)))
; __device__ __forceinline__ unsigned f2bf(float f) { unsigned u = __float_as_uint(f); return (u + 0x7fffu + ((u >> 16) & 1u)) >> 16; }
; __device__ __forceinline__ float bf2f(unsigned h) { return __uint_as_float(h << 16); }
; #define MFMA16(a, b, c) __builtin_amdgcn_mfma_f32_16x16x32_bf16((a), (b), (c), 0, 0, 0)
; __device__ __forceinline__ void hg_b_item(const Params& p, LAS unsigned char* lds, int item, bool dry = false) {
;     ...
;         for (int c2 = 0; c2 < 2; ++c2) { const int g = wave + 8 * c2, nB = 16 * G16 + g; const size_t roB = (size_t)nB * 64 * ZW;
;             bf16x8 bS[4];
; #pragma unroll
;             for (int k = 0; k < 4; ++k) bS[k] = *(const LAS bf16x8*)(SB + g * 2176 + fr * 136 + 32 * k + 8 * fq);
; #pragma unroll
;             for (int lt = 0; lt < 4; ++lt) { f32x4 acc = (f32x4){0.f, 0.f, 0.f, 0.f}; unsigned short oO[4];
; #pragma unroll
;                 for (int r = 0; r < 4; ++r) oO[r] = pO[(size_t)(nB * 64 + 16 * lt + r) * D];
; #pragma unroll
;                 for (int k = 0; k < 4; ++k) { const bf16x8 a = *(const bf16x8*)(pQ + roB + (size_t)(16 * lt) * ZW + 32 * k); acc = MFMA16(a, bS[k], acc); }
; #pragma unroll
;                 for (int r = 0; r < 4; ++r) { const float nv = bf2f(oO[r]) + acc[r]; if (!dry) pO[(size_t)(nB * 64 + 16 * lt + r) * D] = (bf16_t)f2bf(nv); else if (nv == 123456.0f) pO[0] = 0; } } }
	ds_read_b128 v[56:59], v182
	ds_read_b128 v[60:63], v183
	ds_read_b128 v[64:67], v184
	ds_read_b128 v[68:71], v185
	s_waitcnt lgkmcnt(0)
	v_mfma_f32_16x16x32_bf16 v[72:75], v[56:59], v[40:43], 0
	v_mfma_f32_16x16x32_bf16 v[72:75], v[60:63], v[44:47], v[72:75]
	v_mfma_f32_16x16x32_bf16 v[72:75], v[64:67], v[48:51], v[72:75]
	v_mfma_f32_16x16x32_bf16 v[72:75], v[68:71], v[52:55], v[72:75]
	v_lshlrev_b32_e32 v100, 16, v100
	v_lshlrev_b32_e32 v101, 16, v101
	v_lshlrev_b32_e32 v102, 16, v102
	v_lshlrev_b32_e32 v103, 16, v103
	s_nop 7
	v_add_f32_e32 v112, v72, v100
	v_add_f32_e32 v113, v73, v101
	v_add_f32_e32 v114, v74, v102
	v_add_f32_e32 v115, v75, v103
	v_bfe_u32 v116, v112, 16, 1
	v_bfe_u32 v117, v113, 16, 1
	v_bfe_u32 v118, v114, 16, 1
	v_bfe_u32 v119, v115, 16, 1
	v_add3_u32 v112, v112, v116, s27
	v_add3_u32 v113, v113, v117, s27
	v_add3_u32 v114, v114, v118, s27
	v_add3_u32 v115, v115, v119, s27
	global_store_short_d16_hi v[108:109], v112, off offset:-4096
	global_store_short_d16_hi v[108:109], v113, off offset:-2048
	global_store_short_d16_hi v[108:109], v114, off
	global_store_short_d16_hi v[108:109], v115, off offset:2048
	s_add_u32 s60, s54, 0x600000
	s_addc_u32 s61, s55, 0
	s_add_i32 m0, s58, 0x0
	s_nop 0
	global_load_lds_dwordx4 v178, s[60:61]
	s_add_i32 m0, s58, 0x400
	s_nop 0
	global_load_lds_dwordx4 v179, s[60:61]
	s_add_i32 m0, s58, 0x800
	s_nop 0
	global_load_lds_dwordx4 v180, s[60:61]
	s_add_i32 m0, s58, 0xc00
	s_nop 0
	global_load_lds_dwordx4 v181, s[60:61]
	s_add_u32 s16, s56, 0x100000
	s_addc_u32 s17, s57, 0
	v_lshl_add_u64 v[108:109], v[26:27], 0, s[16:17]
	global_load_ushort v100, v[108:109], off offset:-4096
	global_load_ushort v101, v[108:109], off offset:-2048
	global_load_ushort v102, v[108:109], off
	global_load_ushort v103, v[108:109], off offset:2048
	s_waitcnt vmcnt(12)
	ds_read_b128 v[56:59], v182 offset:4096
	ds_read_b128 v[60:63], v183 offset:4096
	ds_read_b128 v[64:67], v184 offset:4096
	ds_read_b128 v[68:71], v185 offset:4096
	s_waitcnt lgkmcnt(0)
	v_mfma_f32_16x16x32_bf16 v[72:75], v[56:59], v[40:43], 0
	v_mfma_f32_16x16x32_bf16 v[72:75], v[60:63], v[44:47], v[72:75]
	v_mfma_f32_16x16x32_bf16 v[72:75], v[64:67], v[48:51], v[72:75]
	v_mfma_f32_16x16x32_bf16 v[72:75], v[68:71], v[52:55], v[72:75]
	v_lshlrev_b32_e32 v104, 16, v104
	v_lshlrev_b32_e32 v105, 16, v105
	v_lshlrev_b32_e32 v106, 16, v106
	v_lshlrev_b32_e32 v107, 16, v107
	s_nop 7
	v_add_f32_e32 v112, v72, v104
	v_add_f32_e32 v113, v73, v105
	v_add_f32_e32 v114, v74, v106
	v_add_f32_e32 v115, v75, v107
	v_bfe_u32 v116, v112, 16, 1
	v_bfe_u32 v117, v113, 16, 1
	v_bfe_u32 v118, v114, 16, 1
	v_bfe_u32 v119, v115, 16, 1
	v_add3_u32 v112, v112, v116, s27
	v_add3_u32 v113, v113, v117, s27
	v_add3_u32 v114, v114, v118, s27
	v_add3_u32 v115, v115, v119, s27
	global_store_short_d16_hi v[110:111], v112, off offset:-4096
	global_store_short_d16_hi v[110:111], v113, off offset:-2048
	global_store_short_d16_hi v[110:111], v114, off
	global_store_short_d16_hi v[110:111], v115, off offset:2048
	s_add_u32 s60, s54, 0x630000
	s_addc_u32 s61, s55, 0
	s_add_i32 m0, s58, 0x1000
	s_nop 0
	global_load_lds_dwordx4 v178, s[60:61]
	s_add_i32 m0, s58, 0x1400
	s_nop 0
	global_load_lds_dwordx4 v179, s[60:61]
	s_add_i32 m0, s58, 0x1800
	s_nop 0
	global_load_lds_dwordx4 v180, s[60:61]
	s_add_i32 m0, s58, 0x1c00
	s_nop 0
	global_load_lds_dwordx4 v181, s[60:61]
	s_add_u32 s16, s56, 0x108000
	s_addc_u32 s17, s57, 0
	v_lshl_add_u64 v[110:111], v[26:27], 0, s[16:17]
	global_load_ushort v104, v[110:111], off offset:-4096
	global_load_ushort v105, v[110:111], off offset:-2048
	global_load_ushort v106, v[110:111], off
	global_load_ushort v107, v[110:111], off offset:2048
	ds_read_b128 v[40:43], v38 offset:34816
	ds_read_b128 v[44:47], v38 offset:34880
	ds_read_b128 v[48:51], v38 offset:34944
	ds_read_b128 v[52:55], v38 offset:35008
	s_waitcnt vmcnt(12)
	ds_read_b128 v[56:59], v182
	ds_read_b128 v[60:63], v183
	ds_read_b128 v[64:67], v184
	ds_read_b128 v[68:71], v185
	s_waitcnt lgkmcnt(0)
	v_mfma_f32_16x16x32_bf16 v[72:75], v[56:59], v[40:43], 0
	v_mfma_f32_16x16x32_bf16 v[72:75], v[60:63], v[44:47], v[72:75]
	v_mfma_f32_16x16x32_bf16 v[72:75], v[64:67], v[48:51], v[72:75]
	v_mfma_f32_16x16x32_bf16 v[72:75], v[68:71], v[52:55], v[72:75]
	v_lshlrev_b32_e32 v100, 16, v100
	v_lshlrev_b32_e32 v101, 16, v101
	v_lshlrev_b32_e32 v102, 16, v102
	v_lshlrev_b32_e32 v103, 16, v103
	s_nop 7
	v_add_f32_e32 v112, v72, v100
	v_add_f32_e32 v113, v73, v101
	v_add_f32_e32 v114, v74, v102
	v_add_f32_e32 v115, v75, v103
	v_bfe_u32 v116, v112, 16, 1
	v_bfe_u32 v117, v113, 16, 1
	v_bfe_u32 v118, v114, 16, 1
	v_bfe_u32 v119, v115, 16, 1
	v_add3_u32 v112, v112, v116, s27
	v_add3_u32 v113, v113, v117, s27
	v_add3_u32 v114, v114, v118, s27
	v_add3_u32 v115, v115, v119, s27
	global_store_short_d16_hi v[108:109], v112, off offset:-4096
	global_store_short_d16_hi v[108:109], v113, off offset:-2048
	global_store_short_d16_hi v[108:109], v114, off
	global_store_short_d16_hi v[108:109], v115, off offset:2048
	s_add_u32 s60, s54, 0x660000
	s_addc_u32 s61, s55, 0
	s_add_i32 m0, s58, 0x0
	s_nop 0
	global_load_lds_dwordx4 v178, s[60:61]
	s_add_i32 m0, s58, 0x400
	s_nop 0
	global_load_lds_dwordx4 v179, s[60:61]
	s_add_i32 m0, s58, 0x800
	s_nop 0
	global_load_lds_dwordx4 v180, s[60:61]
	s_add_i32 m0, s58, 0xc00
	s_nop 0
	global_load_lds_dwordx4 v181, s[60:61]
	s_add_u32 s16, s56, 0x110000
	s_addc_u32 s17, s57, 0
	v_lshl_add_u64 v[108:109], v[26:27], 0, s[16:17]
	global_load_ushort v100, v[108:109], off offset:-4096
	global_load_ushort v101, v[108:109], off offset:-2048
	global_load_ushort v102, v[108:109], off
	global_load_ushort v103, v[108:109], off offset:2048
	s_waitcnt vmcnt(12)
; #define LAS __attribute__((address_space(3)))
; __device__ __forceinline__ unsigned f2bf(float f) { unsigned u = __float_as_uint(f); return (u + 0x7fffu + ((u >> 16) & 1u)) >> 16; }
; __device__ __forceinline__ float bf2f(unsigned h) { return __uint_as_float(h << 16); }
; #define MFMA16(a, b, c) __builtin_amdgcn_mfma_f32_16x16x32_bf16((a), (b), (c), 0, 0, 0)
; __device__ __forceinline__ void hg_b_item(const Params& p, LAS unsigned char* lds, int item, bool dry = false) {
;     ...
;         for (int c2 = 0; c2 < 2; ++c2) { const int g = wave + 8 * c2, nB = 16 * G16 + g; const size_t roB = (size_t)nB * 64 * ZW;
;             bf16x8 bS[4];
; #pragma unroll
;             for (int k = 0; k < 4; ++k) bS[k] = *(const LAS bf16x8*)(SB + g * 2176 + fr * 136 + 32 * k + 8 * fq);
; #pragma unroll
;             for (int lt = 0; lt < 4; ++lt) { f32x4 acc = (f32x4){0.f, 0.f, 0.f, 0.f}; unsigned short oO[4];
; #pragma unroll
;                 for (int r = 0; r < 4; ++r) oO[r] = pO[(size_t)(nB * 64 + 16 * lt + r) * D];
; #pragma unroll
;                 for (int k = 0; k < 4; ++k) { const bf16x8 a = *(const bf16x8*)(pQ + roB + (size_t)(16 * lt) * ZW + 32 * k); acc = MFMA16(a, bS[k], acc); }
; #pragma unroll
;                 for (int r = 0; r < 4; ++r) { const float nv = bf2f(oO[r]) + acc[r]; if (!dry) pO[(size_t)(nB * 64 + 16 * lt + r) * D] = (bf16_t)f2bf(nv); else if (nv == 123456.0f) pO[0] = 0; } } }
;         asm volatile("s_waitcnt lgkmcnt(0)" ::: "memory"); __builtin_amdgcn_s_barrier(); asm volatile("" ::: "memory");
	ds_read_b128 v[56:59], v182 offset:4096
	ds_read_b128 v[60:63], v183 offset:4096
	ds_read_b128 v[64:67], v184 offset:4096
	ds_read_b128 v[68:71], v185 offset:4096
	s_waitcnt lgkmcnt(0)
	v_mfma_f32_16x16x32_bf16 v[72:75], v[56:59], v[40:43], 0
	v_mfma_f32_16x16x32_bf16 v[72:75], v[60:63], v[44:47], v[72:75]
	v_mfma_f32_16x16x32_bf16 v[72:75], v[64:67], v[48:51], v[72:75]
	v_mfma_f32_16x16x32_bf16 v[72:75], v[68:71], v[52:55], v[72:75]
	v_lshlrev_b32_e32 v104, 16, v104
	v_lshlrev_b32_e32 v105, 16, v105
	v_lshlrev_b32_e32 v106, 16, v106
	v_lshlrev_b32_e32 v107, 16, v107
	s_nop 7
	v_add_f32_e32 v112, v72, v104
	v_add_f32_e32 v113, v73, v105
	v_add_f32_e32 v114, v74, v106
	v_add_f32_e32 v115, v75, v107
	v_bfe_u32 v116, v112, 16, 1
	v_bfe_u32 v117, v113, 16, 1
	v_bfe_u32 v118, v114, 16, 1
	v_bfe_u32 v119, v115, 16, 1
	v_add3_u32 v112, v112, v116, s27
	v_add3_u32 v113, v113, v117, s27
	v_add3_u32 v114, v114, v118, s27
	v_add3_u32 v115, v115, v119, s27
	global_store_short_d16_hi v[110:111], v112, off offset:-4096
	global_store_short_d16_hi v[110:111], v113, off offset:-2048
	global_store_short_d16_hi v[110:111], v114, off
	global_store_short_d16_hi v[110:111], v115, off offset:2048
	s_add_u32 s60, s54, 0x690000
	s_addc_u32 s61, s55, 0
	s_add_i32 m0, s58, 0x1000
	s_nop 0
	global_load_lds_dwordx4 v178, s[60:61]
	s_add_i32 m0, s58, 0x1400
	s_nop 0
	global_load_lds_dwordx4 v179, s[60:61]
	s_add_i32 m0, s58, 0x1800
	s_nop 0
	global_load_lds_dwordx4 v180, s[60:61]
	s_add_i32 m0, s58, 0x1c00
	s_nop 0
	global_load_lds_dwordx4 v181, s[60:61]
	s_add_u32 s16, s56, 0x118000
	s_addc_u32 s17, s57, 0
	v_lshl_add_u64 v[110:111], v[26:27], 0, s[16:17]
	global_load_ushort v104, v[110:111], off offset:-4096
	global_load_ushort v105, v[110:111], off offset:-2048
	global_load_ushort v106, v[110:111], off
	global_load_ushort v107, v[110:111], off offset:2048
	s_waitcnt vmcnt(12)
	ds_read_b128 v[56:59], v182
	ds_read_b128 v[60:63], v183
	ds_read_b128 v[64:67], v184
	ds_read_b128 v[68:71], v185
	s_waitcnt lgkmcnt(0)
	v_mfma_f32_16x16x32_bf16 v[72:75], v[56:59], v[40:43], 0
	v_mfma_f32_16x16x32_bf16 v[72:75], v[60:63], v[44:47], v[72:75]
	v_mfma_f32_16x16x32_bf16 v[72:75], v[64:67], v[48:51], v[72:75]
	v_mfma_f32_16x16x32_bf16 v[72:75], v[68:71], v[52:55], v[72:75]
	v_lshlrev_b32_e32 v100, 16, v100
	v_lshlrev_b32_e32 v101, 16, v101
	v_lshlrev_b32_e32 v102, 16, v102
	v_lshlrev_b32_e32 v103, 16, v103
	s_nop 7
	v_add_f32_e32 v112, v72, v100
	v_add_f32_e32 v113, v73, v101
	v_add_f32_e32 v114, v74, v102
	v_add_f32_e32 v115, v75, v103
	v_bfe_u32 v116, v112, 16, 1
	v_bfe_u32 v117, v113, 16, 1
	v_bfe_u32 v118, v114, 16, 1
	v_bfe_u32 v119, v115, 16, 1
	v_add3_u32 v112, v112, v116, s27
	v_add3_u32 v113, v113, v117, s27
	v_add3_u32 v114, v114, v118, s27
	v_add3_u32 v115, v115, v119, s27
	global_store_short_d16_hi v[108:109], v112, off offset:-4096
	global_store_short_d16_hi v[108:109], v113, off offset:-2048
	global_store_short_d16_hi v[108:109], v114, off
	global_store_short_d16_hi v[108:109], v115, off offset:2048
	s_waitcnt vmcnt(4)
	ds_read_b128 v[56:59], v182 offset:4096
	ds_read_b128 v[60:63], v183 offset:4096
	ds_read_b128 v[64:67], v184 offset:4096
	ds_read_b128 v[68:71], v185 offset:4096
	s_waitcnt lgkmcnt(0)
	v_mfma_f32_16x16x32_bf16 v[72:75], v[56:59], v[40:43], 0
	v_mfma_f32_16x16x32_bf16 v[72:75], v[60:63], v[44:47], v[72:75]
	v_mfma_f32_16x16x32_bf16 v[72:75], v[64:67], v[48:51], v[72:75]
	v_mfma_f32_16x16x32_bf16 v[72:75], v[68:71], v[52:55], v[72:75]
	v_lshlrev_b32_e32 v104, 16, v104
	v_lshlrev_b32_e32 v105, 16, v105
	v_lshlrev_b32_e32 v106, 16, v106
	v_lshlrev_b32_e32 v107, 16, v107
	s_nop 7
	v_add_f32_e32 v112, v72, v104
	v_add_f32_e32 v113, v73, v105
	v_add_f32_e32 v114, v74, v106
	v_add_f32_e32 v115, v75, v107
	v_bfe_u32 v116, v112, 16, 1
	v_bfe_u32 v117, v113, 16, 1
	v_bfe_u32 v118, v114, 16, 1
	v_bfe_u32 v119, v115, 16, 1
	v_add3_u32 v112, v112, v116, s27
	v_add3_u32 v113, v113, v117, s27
	v_add3_u32 v114, v114, v118, s27
	v_add3_u32 v115, v115, v119, s27
	global_store_short_d16_hi v[110:111], v112, off offset:-4096
	global_store_short_d16_hi v[110:111], v113, off offset:-2048
	global_store_short_d16_hi v[110:111], v114, off
	global_store_short_d16_hi v[110:111], v115, off offset:2048
	s_barrier
	ds_write_b128 v171, v[80:83]
	ds_write_b128 v171, v[84:87] offset:17408
	ds_write_b128 v171, v[88:91] offset:34816
	ds_write_b128 v171, v[92:95] offset:52224
	s_cmp_eq_u32 s8, 4
	s_waitcnt lgkmcnt(0)
	s_barrier
	s_cbranch_scc0 .LBB0_203
	s_add_i32 s50, s50, s52
	s_cmpk_gt_i32 s50, 0xff
	s_cbranch_scc0 .LBB0_202
